# A2 loop: 2-wait-state pads before the row-sum permlane swaps removed (their operands are no longer freshly written after the packing swaps were deleted)
# speedup vs baseline: 1.0020x; 1.0009x over previous
; __device__ __forceinline__ void softmax_tile(f32x16& p0, f32x16& p1, float& m, float& l, float& alpha, float cb, bf16x8& pa0, bf16x8& pa1, bf16x8& pa2, bf16x8& pa3) {
;     ...
;   for (int r = 0; r < 16; ++r) p0[r] = __builtin_amdgcn_exp2f(p0[r] + off);
; #pragma unroll
;   for (int r = 0; r < 16; ++r) p1[r] = __builtin_amdgcn_exp2f(p1[r] + off);
;   float sm_[4] = {p0[0], p0[1], p0[2], p0[3]};
; #pragma unroll
;   for (int r = 4; r < 16; ++r) sm_[r & 3] += p0[r];
; #pragma unroll
;   for (int r = 0; r < 16; ++r) sm_[r & 3] += p1[r];
;   float ps = (sm_[0] + sm_[1]) + (sm_[2] + sm_[3]);
;   { auto rr = __builtin_amdgcn_permlane32_swap(__float_as_uint(ps), __float_as_uint(ps), false, false);
;     ps = __uint_as_float(rr[0]) + __uint_as_float(rr[1]); }
;   l = l * alpha + ps;
;     ...
;   PK4(p0, 0, pa0); PK4(p0, 8, pa1); PK4(p1, 0, pa2); PK4(p1, 8, pa3);
.Lmy_A_back0:
	v_exp_f32_e32 v3, v160
	v_exp_f32_e32 v4, v161
	v_exp_f32_e32 v5, v162
	v_exp_f32_e32 v6, v163
	v_exp_f32_e32 v7, v164
	v_exp_f32_e32 v8, v165
	v_exp_f32_e32 v9, v166
	v_exp_f32_e32 v10, v167
	v_exp_f32_e32 v11, v168
	v_exp_f32_e32 v12, v169
	v_exp_f32_e32 v13, v170
	v_exp_f32_e32 v160, v171
	v_exp_f32_e32 v161, v172
	v_exp_f32_e32 v162, v173
	v_exp_f32_e32 v163, v174
	v_exp_f32_e32 v164, v175
	v_exp_f32_e32 v144, v144
	v_exp_f32_e32 v145, v145
	v_exp_f32_e32 v146, v146
	v_exp_f32_e32 v147, v147
	v_exp_f32_e32 v148, v148
	v_exp_f32_e32 v149, v149
	v_exp_f32_e32 v150, v150
	v_exp_f32_e32 v151, v151
	v_exp_f32_e32 v159, v159
	v_add_f32_e32 v2, v7, v3
	v_add_f32_e32 v165, v8, v4
	v_add_f32_e32 v166, v9, v5
	v_add_f32_e32 v167, v10, v6
	v_exp_f32_e32 v152, v152
	v_exp_f32_e32 v153, v153
	v_exp_f32_e32 v154, v154
	v_exp_f32_e32 v155, v155
	v_add_f32_e32 v2, v11, v2
	v_add_f32_e32 v165, v12, v165
	v_add_f32_e32 v166, v13, v166
	v_add_f32_e32 v167, v160, v167
	v_exp_f32_e32 v156, v156
	v_exp_f32_e32 v157, v157
	v_exp_f32_e32 v158, v158
	v_add_f32_e32 v2, v161, v2
	v_add_f32_e32 v165, v162, v165
	v_add_f32_e32 v166, v163, v166
	v_add_f32_e32 v167, v164, v167
	v_add_f32_e32 v2, v144, v2
	v_add_f32_e32 v165, v145, v165
	v_add_f32_e32 v166, v146, v166
	v_add_f32_e32 v167, v147, v167
	v_add_f32_e32 v2, v148, v2
	v_add_f32_e32 v165, v149, v165
	v_add_f32_e32 v166, v150, v166
	v_add_f32_e32 v167, v151, v167
	v_add_f32_e32 v2, v152, v2
	v_add_f32_e32 v165, v153, v165
	v_add_f32_e32 v166, v154, v166
	v_add_f32_e32 v167, v155, v167
	v_add_f32_e32 v2, v156, v2
	v_add_f32_e32 v165, v157, v165
	v_add_f32_e32 v166, v158, v166
	v_add_f32_e32 v167, v159, v167
	v_add_f32_e32 v2, v2, v165
	v_add_f32_e32 v165, v166, v167
	v_add_f32_e32 v220, v2, v165
	v_mov_b32_e32 v221, v220
	v_cvt_pk_bf16_f32 v2, v3, v4
	v_cvt_pk_bf16_f32 v3, v5, v6
	v_cvt_pk_bf16_f32 v4, v7, v8
	v_cvt_pk_bf16_f32 v5, v9, v10
	v_cvt_pk_bf16_f32 v6, v11, v12
	v_cvt_pk_bf16_f32 v7, v13, v160
	v_cvt_pk_bf16_f32 v8, v161, v162
	v_cvt_pk_bf16_f32 v9, v163, v164
	v_cvt_pk_bf16_f32 v10, v144, v145
	v_cvt_pk_bf16_f32 v11, v146, v147
	v_cvt_pk_bf16_f32 v12, v148, v149
	v_cvt_pk_bf16_f32 v13, v150, v151
	v_cvt_pk_bf16_f32 v144, v152, v153
	v_cvt_pk_bf16_f32 v145, v154, v155
	v_cvt_pk_bf16_f32 v146, v156, v157
	v_cvt_pk_bf16_f32 v147, v158, v159
	v_permlane32_swap_b32_e32 v220, v221
	v_cmp_gt_f32_e32 vcc, 1.0, v15
	s_cbranch_vccz .LBB0_341
	s_and_saveexec_b64 s[8:9], s[4:5]
	ds_write_b32 v215, v15
	s_or_b64 exec, exec, s[8:9]
	s_waitcnt lgkmcnt(0)
	ds_read_b128 v[148:151], v216 offset:96
	ds_read_b128 v[152:155], v216 offset:64
	ds_read_b128 v[156:159], v216 offset:32
	ds_read_b128 v[160:163], v216
	s_waitcnt lgkmcnt(3)
	v_pk_mul_f32 v[142:143], v[142:143], v[150:151]
	s_waitcnt lgkmcnt(2)
	v_pk_mul_f32 v[138:139], v[138:139], v[154:155]
	s_waitcnt lgkmcnt(1)
	v_pk_mul_f32 v[134:135], v[134:135], v[158:159]
	s_waitcnt lgkmcnt(0)
	v_pk_mul_f32 v[130:131], v[130:131], v[162:163]
	v_pk_mul_f32 v[140:141], v[140:141], v[148:149]
	v_pk_mul_f32 v[136:137], v[136:137], v[152:153]
	v_pk_mul_f32 v[132:133], v[132:133], v[156:157]
	v_pk_mul_f32 v[128:129], v[128:129], v[160:161]
	v_pk_mul_f32 v[110:111], v[110:111], v[150:151]
	v_pk_mul_f32 v[106:107], v[106:107], v[154:155]
	v_pk_mul_f32 v[102:103], v[102:103], v[158:159]
	v_pk_mul_f32 v[98:99], v[98:99], v[162:163]
	v_pk_mul_f32 v[108:109], v[108:109], v[148:149]
	v_pk_mul_f32 v[104:105], v[104:105], v[152:153]
	v_pk_mul_f32 v[100:101], v[100:101], v[156:157]
	v_pk_mul_f32 v[96:97], v[96:97], v[160:161]
	v_pk_mul_f32 v[62:63], v[62:63], v[150:151]
	v_pk_mul_f32 v[58:59], v[58:59], v[154:155]
	v_pk_mul_f32 v[54:55], v[54:55], v[158:159]
	v_pk_mul_f32 v[50:51], v[50:51], v[162:163]
	v_pk_mul_f32 v[60:61], v[60:61], v[148:149]
	v_pk_mul_f32 v[56:57], v[56:57], v[152:153]
	v_pk_mul_f32 v[52:53], v[52:53], v[156:157]
	v_pk_mul_f32 v[48:49], v[48:49], v[160:161]
	v_pk_mul_f32 v[94:95], v[94:95], v[150:151]
	v_pk_mul_f32 v[90:91], v[90:91], v[154:155]
	v_pk_mul_f32 v[86:87], v[86:87], v[158:159]
	v_pk_mul_f32 v[82:83], v[82:83], v[162:163]
	v_pk_mul_f32 v[92:93], v[92:93], v[148:149]
	v_pk_mul_f32 v[88:89], v[88:89], v[152:153]
	v_pk_mul_f32 v[84:85], v[84:85], v[156:157]
	v_pk_mul_f32 v[80:81], v[80:81], v[160:161]

; __device__ __forceinline__ void softmax_tile(f32x16& p0, f32x16& p1, float& m, float& l, float& alpha, float cb, bf16x8& pa0, bf16x8& pa1, bf16x8& pa2, bf16x8& pa3) {
;     ...
;   for (int r = 0; r < 16; ++r) p0[r] = __builtin_amdgcn_exp2f(p0[r] + off);
; #pragma unroll
;   for (int r = 0; r < 16; ++r) p1[r] = __builtin_amdgcn_exp2f(p1[r] + off);
;   float sm_[4] = {p0[0], p0[1], p0[2], p0[3]};
; #pragma unroll
;   for (int r = 4; r < 16; ++r) sm_[r & 3] += p0[r];
; #pragma unroll
;   for (int r = 0; r < 16; ++r) sm_[r & 3] += p1[r];
;   float ps = (sm_[0] + sm_[1]) + (sm_[2] + sm_[3]);
;   { auto rr = __builtin_amdgcn_permlane32_swap(__float_as_uint(ps), __float_as_uint(ps), false, false);
;     ps = __uint_as_float(rr[0]) + __uint_as_float(rr[1]); }
;   l = l * alpha + ps;
;     ...
;   PK4(p0, 0, pa0); PK4(p0, 8, pa1); PK4(p1, 0, pa2); PK4(p1, 8, pa3);
.Lmy_A_back1:
	v_exp_f32_e32 v8, v165
	v_exp_f32_e32 v9, v166
	v_exp_f32_e32 v165, v148
	v_exp_f32_e32 v166, v149
	v_exp_f32_e32 v150, v150
	v_exp_f32_e32 v151, v151
	v_exp_f32_e32 v152, v152
	v_exp_f32_e32 v153, v153
	v_exp_f32_e32 v3, v160
	v_exp_f32_e32 v4, v161
	v_exp_f32_e32 v5, v162
	v_exp_f32_e32 v6, v163
	v_exp_f32_e32 v7, v164
	v_exp_f32_e32 v10, v167
	v_exp_f32_e32 v154, v154
	v_exp_f32_e32 v11, v168
	v_exp_f32_e32 v12, v169
	v_exp_f32_e32 v13, v170
	v_exp_f32_e32 v160, v171
	v_exp_f32_e32 v155, v155
	v_exp_f32_e32 v161, v172
	v_exp_f32_e32 v162, v173
	v_exp_f32_e32 v163, v174
	v_exp_f32_e32 v164, v175
	v_exp_f32_e32 v156, v156
	v_exp_f32_e32 v144, v144
	v_exp_f32_e32 v145, v145
	v_exp_f32_e32 v146, v146
	v_exp_f32_e32 v147, v147
	v_exp_f32_e32 v157, v157
	v_exp_f32_e32 v158, v158
	v_exp_f32_e32 v159, v159
	v_add_f32_e32 v2, v7, v3
	v_add_f32_e32 v148, v8, v4
	v_add_f32_e32 v149, v9, v5
	v_add_f32_e32 v167, v10, v6
	v_add_f32_e32 v2, v11, v2
	v_add_f32_e32 v148, v12, v148
	v_add_f32_e32 v149, v13, v149
	v_add_f32_e32 v167, v160, v167
	v_add_f32_e32 v2, v161, v2
	v_add_f32_e32 v148, v162, v148
	v_add_f32_e32 v149, v163, v149
	v_add_f32_e32 v167, v164, v167
	v_add_f32_e32 v2, v144, v2
	v_add_f32_e32 v148, v145, v148
	v_add_f32_e32 v149, v146, v149
	v_add_f32_e32 v167, v147, v167
	v_add_f32_e32 v2, v165, v2
	v_add_f32_e32 v148, v166, v148
	v_add_f32_e32 v149, v150, v149
	v_add_f32_e32 v167, v151, v167
	v_add_f32_e32 v2, v152, v2
	v_add_f32_e32 v148, v153, v148
	v_add_f32_e32 v149, v154, v149
	v_add_f32_e32 v167, v155, v167
	v_add_f32_e32 v2, v156, v2
	v_add_f32_e32 v148, v157, v148
	v_add_f32_e32 v149, v158, v149
	v_add_f32_e32 v167, v159, v167
	v_add_f32_e32 v2, v2, v148
	v_add_f32_e32 v148, v149, v167
	v_add_f32_e32 v148, v2, v148
	v_mov_b32_e32 v149, v148
	v_cvt_pk_bf16_f32 v2, v3, v4
	v_cvt_pk_bf16_f32 v3, v5, v6
	v_cvt_pk_bf16_f32 v4, v7, v8
	v_cvt_pk_bf16_f32 v5, v9, v10
	v_cvt_pk_bf16_f32 v6, v11, v12
	v_cvt_pk_bf16_f32 v7, v13, v160
	v_cvt_pk_bf16_f32 v8, v161, v162
	v_cvt_pk_bf16_f32 v9, v163, v164
	v_cvt_pk_bf16_f32 v10, v144, v145
	v_cvt_pk_bf16_f32 v11, v146, v147
	v_cvt_pk_bf16_f32 v12, v165, v166
	v_cvt_pk_bf16_f32 v13, v150, v151
	v_cvt_pk_bf16_f32 v144, v152, v153
	v_cvt_pk_bf16_f32 v145, v154, v155
	v_cvt_pk_bf16_f32 v146, v156, v157
	v_cvt_pk_bf16_f32 v147, v158, v159
	v_permlane32_swap_b32_e32 v148, v149
	v_cmp_gt_f32_e32 vcc, 1.0, v223
	s_cbranch_vccz .LBB0_347
	s_and_saveexec_b64 s[6:7], s[4:5]
	ds_write_b32 v215, v223 offset:128
	s_or_b64 exec, exec, s[6:7]
	s_waitcnt lgkmcnt(0)
	ds_read_b128 v[150:153], v216 offset:224
	ds_read_b128 v[154:157], v216 offset:192
	ds_read_b128 v[158:161], v216 offset:160
	ds_read_b128 v[162:165], v216 offset:128
	s_waitcnt lgkmcnt(3)
	v_pk_mul_f32 v[126:127], v[126:127], v[152:153]
	s_waitcnt lgkmcnt(2)
	v_pk_mul_f32 v[122:123], v[122:123], v[156:157]
	s_waitcnt lgkmcnt(1)
	v_pk_mul_f32 v[118:119], v[118:119], v[160:161]
	s_waitcnt lgkmcnt(0)
	v_pk_mul_f32 v[114:115], v[114:115], v[164:165]
	v_pk_mul_f32 v[124:125], v[124:125], v[150:151]
	v_pk_mul_f32 v[120:121], v[120:121], v[154:155]
	v_pk_mul_f32 v[116:117], v[116:117], v[158:159]
	v_pk_mul_f32 v[112:113], v[112:113], v[162:163]
	v_pk_mul_f32 v[78:79], v[78:79], v[152:153]
	v_pk_mul_f32 v[74:75], v[74:75], v[156:157]
	v_pk_mul_f32 v[70:71], v[70:71], v[160:161]
	v_pk_mul_f32 v[66:67], v[66:67], v[164:165]
	v_pk_mul_f32 v[76:77], v[76:77], v[150:151]
	v_pk_mul_f32 v[72:73], v[72:73], v[154:155]
	v_pk_mul_f32 v[68:69], v[68:69], v[158:159]
	v_pk_mul_f32 v[64:65], v[64:65], v[162:163]
	v_pk_mul_f32 v[30:31], v[30:31], v[152:153]
	v_pk_mul_f32 v[26:27], v[26:27], v[156:157]
	v_pk_mul_f32 v[22:23], v[22:23], v[160:161]
	v_pk_mul_f32 v[18:19], v[18:19], v[164:165]
	v_pk_mul_f32 v[28:29], v[28:29], v[150:151]
	v_pk_mul_f32 v[24:25], v[24:25], v[154:155]
	v_pk_mul_f32 v[20:21], v[20:21], v[158:159]
	v_pk_mul_f32 v[16:17], v[16:17], v[162:163]
	v_pk_mul_f32 v[46:47], v[46:47], v[152:153]
	v_pk_mul_f32 v[42:43], v[42:43], v[156:157]
	v_pk_mul_f32 v[38:39], v[38:39], v[160:161]
	v_pk_mul_f32 v[34:35], v[34:35], v[164:165]
	v_pk_mul_f32 v[44:45], v[44:45], v[150:151]
	v_pk_mul_f32 v[40:41], v[40:41], v[154:155]
	v_pk_mul_f32 v[36:37], v[36:37], v[158:159]
	v_pk_mul_f32 v[32:33], v[32:33], v[162:163]
